# grid barrier followers: L1-only invalidate; the XCD leader waits for its agent-scope invalidate to complete before republishing the generation word
# baseline (speedup 1.0000x reference)
; __device__ __forceinline__ unsigned xb_ld(unsigned* p)              { return __hip_atomic_load(p, __ATOMIC_RELAXED, __HIP_MEMORY_SCOPE_AGENT); }
; __device__ __forceinline__ unsigned xb_add(unsigned* p, unsigned v) { return __hip_atomic_fetch_add(p, v, __ATOMIC_RELAXED, __HIP_MEMORY_SCOPE_AGENT); }
; #define XB_SPIN(cond, bar) do { unsigned _sp = 0; while (cond) { __builtin_amdgcn_s_sleep(1); \
;     if ((++_sp & 255u) == 0u) { if (xb_ld(&(bar)[XB_TMO])) break; if (_sp > XB_SPIN_CAP) { atomicAdd(&(bar)[XB_TMO], 1u); break; } } } } while (0)
; __device__ __forceinline__ void xcd_barrier(unsigned* bar, volatile LAS unsigned* st, const int tid) {
;     ...
;             const unsigned og = xb_add(&bar[XB_TOP], 1u);
;             const unsigned tg = og / nx;
;             if (og + 1u == (tg + 1u) * nx) xb_add(&bar[XB_TOPGEN], 1u);
;             else XB_SPIN(xb_ld(&bar[XB_TOPGEN]) == tg, bar);
;             __builtin_amdgcn_fence(__ATOMIC_ACQUIRE, "agent");
;             xb_add(&bar[XB_XGEN(x)], 1u);
;             asm volatile("s_waitcnt vmcnt(0)" ::: "memory");
.LBB0_99:
	s_or_b64 exec, exec, s[14:15]
	s_mov_b64 s[14:15], exec
	v_mbcnt_lo_u32_b32 v0, s14, 0
	v_mbcnt_hi_u32_b32 v0, s15, v0
	v_cmp_eq_u32_e32 vcc, 0, v0
	s_waitcnt vmcnt(0) lgkmcnt(0)
	buffer_inv sc1
	s_waitcnt vmcnt(0)
	s_and_saveexec_b64 s[22:23], vcc
	s_cbranch_execz .LBB0_101
	s_bcnt1_i32_b64 s3, s[14:15]
	v_mov_b32_e32 v0, s3
	v_mov_b32_e32 v1, 0x2000
	global_atomic_add v1, v0, s[16:17] offset:1024
